# MLA part1 stage-3: softmax VALU rebalanced (hi-half exp/cvt and row-sum moved into PV MFMA gaps, max chain spread over first QK gaps), mid-step DMA; no residual-epilogue edits
# baseline (speedup 1.0000x reference)
.LBB0_786:
	s_bitcmp1_b32 s2, 0
	s_cselect_b32 s2, 0xa000, 0
	v_add_u32_e32 v96, s2, v95
	ds_read_b128 v[172:175], v96
	ds_read_b128 v[176:179], v96 offset:1024
	ds_read_b128 v[188:191], v96 offset:2048
	ds_read_b128 v[192:195], v96 offset:3072
	ds_read_b128 v[198:201], v96 offset:4096
	ds_read_b128 v[202:205], v96 offset:5120
	s_cmp_eq_u32 s5, 1
	s_cbranch_scc1 .Lmy_first
	s_waitcnt lgkmcnt(5)
	v_mfma_f32_32x32x16_bf16 v[64:79], v[172:175], v[82:85], 0
	ds_read_b128 v[172:175], v96 offset:6144
	v_max_f32_e32 v111, v219, v219
	v_max_f32_e32 v159, v218, v218
	v_max_f32_e32 v111, v159, v111
	v_max3_f32 v111, v111, v220, v221
	v_max3_f32 v111, v111, v222, v223
	v_max3_f32 v111, v111, v224, v225
	v_max3_f32 v111, v111, v226, v227
	s_waitcnt lgkmcnt(5)
	v_mfma_f32_32x32x16_bf16 v[64:79], v[176:179], v[86:89], v[64:79]
	ds_read_b128 v[176:179], v96 offset:7168
	v_max3_f32 v111, v111, v228, v229
	v_max3_f32 v111, v111, v230, v231
	v_max3_f32 v111, v111, v232, v233
	v_mov_b32_e32 v159, v111
	s_nop 1
	v_permlane32_swap_b32_e32 v111, v159
	v_max_f32_e32 v159, v159, v159
	s_waitcnt lgkmcnt(5)
	v_mfma_f32_32x32x16_bf16 v[64:79], v[188:191], v[90:93], v[64:79]
	ds_read_b128 v[188:191], v96 offset:8192
	v_max_f32_e32 v111, v111, v111
	v_max_f32_e32 v111, v111, v159
	v_mul_f32_e32 v111, 0x3dd53b94, v111
	v_cmp_le_f32_e32 vcc, v111, v110
	s_cmp_eq_u64 vcc, exec
	s_cbranch_scc1 .LBB0_790
	v_max_f32_e32 v110, v111, v111
	v_max_f32_e32 v111, v80, v80
	v_max_f32_e32 v111, v111, v110
	v_sub_f32_e32 v80, v80, v111
	v_exp_f32_e32 v80, v80
	v_xor_b32_e32 v110, 0x80000000, v111
	v_mul_f32_e32 v81, v81, v80
	v_pk_mul_f32 v[62:63], v[62:63], v[80:81] op_sel_hi:[1,0]
	v_pk_mul_f32 v[60:61], v[60:61], v[80:81] op_sel_hi:[1,0]
	v_pk_mul_f32 v[58:59], v[58:59], v[80:81] op_sel_hi:[1,0]
	v_pk_mul_f32 v[56:57], v[56:57], v[80:81] op_sel_hi:[1,0]
	v_pk_mul_f32 v[54:55], v[54:55], v[80:81] op_sel_hi:[1,0]
	v_pk_mul_f32 v[52:53], v[52:53], v[80:81] op_sel_hi:[1,0]
	v_pk_mul_f32 v[50:51], v[50:51], v[80:81] op_sel_hi:[1,0]
	v_pk_mul_f32 v[48:49], v[48:49], v[80:81] op_sel_hi:[1,0]
	v_pk_mul_f32 v[46:47], v[46:47], v[80:81] op_sel_hi:[1,0]
	v_pk_mul_f32 v[44:45], v[44:45], v[80:81] op_sel_hi:[1,0]
	v_pk_mul_f32 v[42:43], v[42:43], v[80:81] op_sel_hi:[1,0]
	v_pk_mul_f32 v[40:41], v[40:41], v[80:81] op_sel_hi:[1,0]
	v_pk_mul_f32 v[38:39], v[38:39], v[80:81] op_sel_hi:[1,0]
	v_pk_mul_f32 v[36:37], v[36:37], v[80:81] op_sel_hi:[1,0]
	v_pk_mul_f32 v[34:35], v[34:35], v[80:81] op_sel_hi:[1,0]
	v_pk_mul_f32 v[32:33], v[32:33], v[80:81] op_sel_hi:[1,0]
	v_pk_mul_f32 v[30:31], v[30:31], v[80:81] op_sel_hi:[1,0]
	v_pk_mul_f32 v[28:29], v[28:29], v[80:81] op_sel_hi:[1,0]
	v_pk_mul_f32 v[26:27], v[26:27], v[80:81] op_sel_hi:[1,0]
	v_pk_mul_f32 v[24:25], v[24:25], v[80:81] op_sel_hi:[1,0]
	v_pk_mul_f32 v[22:23], v[22:23], v[80:81] op_sel_hi:[1,0]
	v_pk_mul_f32 v[20:21], v[20:21], v[80:81] op_sel_hi:[1,0]
	v_pk_mul_f32 v[18:19], v[18:19], v[80:81] op_sel_hi:[1,0]
	v_pk_mul_f32 v[16:17], v[16:17], v[80:81] op_sel_hi:[1,0]
	v_pk_mul_f32 v[14:15], v[14:15], v[80:81] op_sel_hi:[1,0]
	v_pk_mul_f32 v[12:13], v[12:13], v[80:81] op_sel_hi:[1,0]
	v_pk_mul_f32 v[10:11], v[10:11], v[80:81] op_sel_hi:[1,0]
	v_pk_mul_f32 v[8:9], v[8:9], v[80:81] op_sel_hi:[1,0]
	v_pk_mul_f32 v[6:7], v[6:7], v[80:81] op_sel_hi:[1,0]
	v_pk_mul_f32 v[4:5], v[4:5], v[80:81] op_sel_hi:[1,0]
	v_pk_mul_f32 v[2:3], v[2:3], v[80:81] op_sel_hi:[1,0]
	v_pk_mul_f32 v[0:1], v[0:1], v[80:81] op_sel_hi:[1,0]
	v_mov_b32_e32 v80, v111
	s_branch .LBB0_791

.LBB0_791:
	s_waitcnt lgkmcnt(5)
	v_mfma_f32_32x32x16_bf16 v[64:79], v[192:195], v[112:115], v[64:79]
	ds_read_b128 v[192:195], v96 offset:9216
	v_fmamk_f32 v218, v218, 0x3dd53b94, v110
	v_fmamk_f32 v219, v219, 0x3dd53b94, v110
	v_exp_f32_e32 v218, v218
	v_fmamk_f32 v220, v220, 0x3dd53b94, v110
	v_exp_f32_e32 v219, v219
	s_waitcnt lgkmcnt(5)
	v_mfma_f32_32x32x16_bf16 v[64:79], v[198:201], v[116:119], v[64:79]
	ds_read_b128 v[198:201], v96 offset:10240
	v_add_f32_e32 v183, 0, v218
	v_fmamk_f32 v221, v221, 0x3dd53b94, v110
	v_exp_f32_e32 v220, v220
	v_add_f32_e32 v183, v219, v183
	v_fmamk_f32 v222, v222, 0x3dd53b94, v110
	s_waitcnt lgkmcnt(5)
	v_mfma_f32_32x32x16_bf16 v[64:79], v[202:205], v[120:123], v[64:79]
	ds_read_b128 v[202:205], v96 offset:11264
	v_exp_f32_e32 v221, v221
	v_add_f32_e32 v183, v220, v183
	v_fmamk_f32 v223, v223, 0x3dd53b94, v110
	v_exp_f32_e32 v222, v222
	v_add_f32_e32 v183, v221, v183
	s_waitcnt lgkmcnt(5)
	v_mfma_f32_32x32x16_bf16 v[64:79], v[172:175], v[124:127], v[64:79]
	ds_read_b128 v[172:175], v96 offset:20480
	v_fmamk_f32 v224, v224, 0x3dd53b94, v110
	v_exp_f32_e32 v223, v223
	v_add_f32_e32 v183, v222, v183
	v_fmamk_f32 v225, v225, 0x3dd53b94, v110
	v_exp_f32_e32 v224, v224
	s_waitcnt lgkmcnt(5)
	v_mfma_f32_32x32x16_bf16 v[64:79], v[176:179], v[128:131], v[64:79]
	ds_read_b128 v[176:179], v96 offset:21504
	v_add_f32_e32 v183, v223, v183
	v_exp_f32_e32 v225, v225
	v_add_f32_e32 v183, v224, v183
	v_add_f32_e32 v183, v225, v183
	v_fmamk_f32 v159, v226, 0x3dd53b94, v110
	s_waitcnt lgkmcnt(5)
	v_mfma_f32_32x32x16_bf16 v[64:79], v[188:191], v[132:135], v[64:79]
	ds_read_b128 v[188:191], v96 offset:22528
	v_fmamk_f32 v111, v227, 0x3dd53b94, v110
	v_fmamk_f32 v165, v228, 0x3dd53b94, v110
	v_fmamk_f32 v166, v229, 0x3dd53b94, v110
	v_cvt_pk_bf16_f32 v218, v218, v219
	v_cvt_pk_bf16_f32 v219, v220, v221
	s_waitcnt lgkmcnt(5)
	v_mfma_f32_32x32x16_bf16 v[64:79], v[192:195], v[136:139], v[64:79]
	ds_read_b128 v[192:195], v96 offset:23552
	v_fmamk_f32 v167, v230, 0x3dd53b94, v110
	v_fmamk_f32 v168, v231, 0x3dd53b94, v110
	v_fmamk_f32 v169, v232, 0x3dd53b94, v110
	v_fmac_f32_e32 v110, 0x3dd53b94, v233
	v_cvt_pk_bf16_f32 v220, v222, v223
	s_waitcnt lgkmcnt(5)
	v_mfma_f32_32x32x16_bf16 v[64:79], v[198:201], v[140:143], v[64:79]
	ds_read_b128 v[198:201], v96 offset:24576
	v_cvt_pk_bf16_f32 v221, v224, v225
	v_exp_f32_e32 v159, v159
	v_exp_f32_e32 v111, v111
	s_waitcnt lgkmcnt(5)
	v_mfma_f32_32x32x16_bf16 v[64:79], v[202:205], v[144:147], v[64:79]
	ds_read_b128 v[202:205], v96 offset:25600
	v_mfma_f32_32x32x16_bf16 v[48:63], v[148:151], v[218:221], v[48:63]
	ds_read_b128 v[148:151], v96 offset:12288
	v_exp_f32_e32 v165, v165
	v_exp_f32_e32 v166, v166
	v_exp_f32_e32 v167, v167
	v_mfma_f32_32x32x16_bf16 v[32:47], v[106:109], v[218:221], v[32:47]
	ds_read_b128 v[106:109], v96 offset:13312
	v_exp_f32_e32 v168, v168
	v_exp_f32_e32 v169, v169
	v_exp_f32_e32 v110, v110
	v_mfma_f32_32x32x16_bf16 v[16:31], v[98:101], v[218:221], v[16:31]
	v_cvt_pk_bf16_f32 v98, v159, v111
	v_cvt_pk_bf16_f32 v99, v165, v166
	v_cvt_pk_bf16_f32 v100, v167, v168
	v_cvt_pk_bf16_f32 v101, v169, v110
	v_mfma_f32_32x32x16_bf16 v[0:15], v[102:105], v[218:221], v[0:15]
	ds_read_b128 v[102:105], v96 offset:15360
	v_add_f32_e32 v183, v159, v183
	v_add_f32_e32 v183, v111, v183
	v_add_f32_e32 v183, v165, v183
	v_add_f32_e32 v183, v166, v183
	v_mfma_f32_32x32x16_bf16 v[48:63], v[234:237], v[98:101], v[48:63]
	v_add_f32_e32 v183, v167, v183
	v_add_f32_e32 v183, v168, v183
	v_add_f32_e32 v183, v169, v183
	v_add_f32_e32 v183, v110, v183
	v_mfma_f32_32x32x16_bf16 v[32:47], v[206:209], v[98:101], v[32:47]
	v_mov_b32_e32 v171, v183
	s_nop 1
	v_permlane32_swap_b32_e32 v183, v171
	v_mfma_f32_32x32x16_bf16 v[16:31], v[238:241], v[98:101], v[16:31]
	v_add_f32_e32 v183, v183, v171
	v_add_f32_e32 v81, v81, v183
	v_mfma_f32_32x32x16_bf16 v[0:15], v[242:245], v[98:101], v[0:15]
	ds_read_b128 v[98:101], v96 offset:14336
	s_branch .Lmy_join

.Lmy_nodma:
	s_waitcnt lgkmcnt(9)
	v_mfma_f32_32x32x16_bf16 v[218:233], v[172:175], v[82:85], 0
	ds_read_b128 v[172:175], v96 offset:26624
	v_max_f32_e32 v110, v65, v65
	v_max_f32_e32 v111, v64, v64
	v_max_f32_e32 v110, v111, v110
	v_max3_f32 v110, v110, v66, v67
	v_max3_f32 v110, v110, v68, v69
	v_max3_f32 v110, v110, v70, v71
	v_max3_f32 v110, v110, v72, v73
	s_waitcnt lgkmcnt(9)
	v_mfma_f32_32x32x16_bf16 v[218:233], v[176:179], v[86:89], v[218:233]
	ds_read_b128 v[176:179], v96 offset:27648
	v_max3_f32 v110, v110, v74, v75
	v_max3_f32 v110, v110, v76, v77
	v_max3_f32 v110, v110, v78, v79
	v_mov_b32_e32 v111, v110
	s_nop 1
	v_permlane32_swap_b32_e32 v110, v111
	v_max_f32_e32 v111, v111, v111
	s_waitcnt lgkmcnt(9)
	v_mfma_f32_32x32x16_bf16 v[218:233], v[188:191], v[90:93], v[218:233]
	ds_read_b128 v[188:191], v96 offset:28672
	v_max_f32_e32 v110, v110, v110
	v_max_f32_e32 v110, v110, v111
	v_mul_f32_e32 v111, 0x3dd53b94, v110
	v_add_f32_e32 v110, 0x41000000, v80
	v_cmp_le_f32_e32 vcc, v111, v110
	s_cmp_eq_u64 vcc, exec
	s_cbranch_scc1 .LBB0_788
	v_max_f32_e32 v110, v111, v111
	v_max_f32_e32 v111, v80, v80
	v_max_f32_e32 v111, v111, v110
	v_sub_f32_e32 v80, v80, v111
	v_exp_f32_e32 v80, v80
	v_add_f32_e32 v110, 0x41000000, v111
	v_mul_f32_e32 v81, v81, v80
	v_pk_mul_f32 v[62:63], v[62:63], v[80:81] op_sel_hi:[1,0]
	v_pk_mul_f32 v[60:61], v[60:61], v[80:81] op_sel_hi:[1,0]
	v_pk_mul_f32 v[58:59], v[58:59], v[80:81] op_sel_hi:[1,0]
	v_pk_mul_f32 v[56:57], v[56:57], v[80:81] op_sel_hi:[1,0]
	v_pk_mul_f32 v[54:55], v[54:55], v[80:81] op_sel_hi:[1,0]
	v_pk_mul_f32 v[52:53], v[52:53], v[80:81] op_sel_hi:[1,0]
	v_pk_mul_f32 v[50:51], v[50:51], v[80:81] op_sel_hi:[1,0]
	v_pk_mul_f32 v[48:49], v[48:49], v[80:81] op_sel_hi:[1,0]
	v_pk_mul_f32 v[46:47], v[46:47], v[80:81] op_sel_hi:[1,0]
	v_pk_mul_f32 v[44:45], v[44:45], v[80:81] op_sel_hi:[1,0]
	v_pk_mul_f32 v[42:43], v[42:43], v[80:81] op_sel_hi:[1,0]
	v_pk_mul_f32 v[40:41], v[40:41], v[80:81] op_sel_hi:[1,0]
	v_pk_mul_f32 v[38:39], v[38:39], v[80:81] op_sel_hi:[1,0]
	v_pk_mul_f32 v[36:37], v[36:37], v[80:81] op_sel_hi:[1,0]
	v_pk_mul_f32 v[34:35], v[34:35], v[80:81] op_sel_hi:[1,0]
	v_pk_mul_f32 v[32:33], v[32:33], v[80:81] op_sel_hi:[1,0]
	v_pk_mul_f32 v[30:31], v[30:31], v[80:81] op_sel_hi:[1,0]
	v_pk_mul_f32 v[28:29], v[28:29], v[80:81] op_sel_hi:[1,0]
	v_pk_mul_f32 v[26:27], v[26:27], v[80:81] op_sel_hi:[1,0]
	v_pk_mul_f32 v[24:25], v[24:25], v[80:81] op_sel_hi:[1,0]
	v_pk_mul_f32 v[22:23], v[22:23], v[80:81] op_sel_hi:[1,0]
	v_pk_mul_f32 v[20:21], v[20:21], v[80:81] op_sel_hi:[1,0]
	v_pk_mul_f32 v[18:19], v[18:19], v[80:81] op_sel_hi:[1,0]
	v_pk_mul_f32 v[16:17], v[16:17], v[80:81] op_sel_hi:[1,0]
	v_pk_mul_f32 v[14:15], v[14:15], v[80:81] op_sel_hi:[1,0]
	v_pk_mul_f32 v[12:13], v[12:13], v[80:81] op_sel_hi:[1,0]
	v_pk_mul_f32 v[10:11], v[10:11], v[80:81] op_sel_hi:[1,0]
	v_pk_mul_f32 v[8:9], v[8:9], v[80:81] op_sel_hi:[1,0]
	v_pk_mul_f32 v[6:7], v[6:7], v[80:81] op_sel_hi:[1,0]
	v_pk_mul_f32 v[4:5], v[4:5], v[80:81] op_sel_hi:[1,0]
	v_pk_mul_f32 v[2:3], v[2:3], v[80:81] op_sel_hi:[1,0]
	v_pk_mul_f32 v[0:1], v[0:1], v[80:81] op_sel_hi:[1,0]
	v_mov_b32_e32 v80, v111
.LBB0_788:
	s_waitcnt lgkmcnt(9)
	v_mfma_f32_32x32x16_bf16 v[218:233], v[192:195], v[112:115], v[218:233]
	ds_read_b128 v[192:195], v96 offset:29696
	v_fma_f32 v64, v64, s80, -v80
	v_fma_f32 v65, v65, s80, -v80
	v_exp_f32_e32 v64, v64
	v_fma_f32 v66, v66, s80, -v80
	v_exp_f32_e32 v65, v65
	s_waitcnt lgkmcnt(9)
	v_mfma_f32_32x32x16_bf16 v[218:233], v[198:201], v[116:119], v[218:233]
	ds_read_b128 v[198:201], v96 offset:30720
	v_add_f32_e32 v183, 0, v64
	v_fma_f32 v67, v67, s80, -v80
	v_exp_f32_e32 v66, v66
	v_add_f32_e32 v183, v65, v183
	v_fma_f32 v68, v68, s80, -v80
	s_waitcnt lgkmcnt(9)
	v_mfma_f32_32x32x16_bf16 v[218:233], v[202:205], v[120:123], v[218:233]
	ds_read_b128 v[202:205], v96 offset:31744
	v_exp_f32_e32 v67, v67
	v_add_f32_e32 v183, v66, v183
	v_fma_f32 v69, v69, s80, -v80
	v_exp_f32_e32 v68, v68
	v_add_f32_e32 v183, v67, v183
	s_waitcnt lgkmcnt(5)
	v_mfma_f32_32x32x16_bf16 v[218:233], v[172:175], v[124:127], v[218:233]
	v_fma_f32 v70, v70, s80, -v80
	v_exp_f32_e32 v69, v69
	v_add_f32_e32 v183, v68, v183
	v_fma_f32 v71, v71, s80, -v80
	v_exp_f32_e32 v70, v70
	s_waitcnt lgkmcnt(4)
	v_mfma_f32_32x32x16_bf16 v[218:233], v[176:179], v[128:131], v[218:233]
	v_add_f32_e32 v183, v69, v183
	v_exp_f32_e32 v71, v71
	v_add_f32_e32 v183, v70, v183
	v_add_f32_e32 v183, v71, v183
	v_fma_f32 v159, v72, s80, -v80
	s_waitcnt lgkmcnt(3)
	v_mfma_f32_32x32x16_bf16 v[218:233], v[188:191], v[132:135], v[218:233]
	v_fma_f32 v111, v73, s80, -v80
	v_fma_f32 v165, v74, s80, -v80
	v_fma_f32 v166, v75, s80, -v80
	v_cvt_pk_bf16_f32 v64, v64, v65
	v_cvt_pk_bf16_f32 v65, v66, v67
	s_waitcnt lgkmcnt(2)
	v_mfma_f32_32x32x16_bf16 v[218:233], v[192:195], v[136:139], v[218:233]
	v_fma_f32 v167, v76, s80, -v80
	v_fma_f32 v168, v77, s80, -v80
	v_fma_f32 v169, v78, s80, -v80
	v_fma_f32 v170, v79, s80, -v80
	v_cvt_pk_bf16_f32 v66, v68, v69
	s_waitcnt lgkmcnt(1)
	v_mfma_f32_32x32x16_bf16 v[218:233], v[198:201], v[140:143], v[218:233]
	v_cvt_pk_bf16_f32 v67, v70, v71
	v_exp_f32_e32 v159, v159
	v_exp_f32_e32 v111, v111
	s_waitcnt lgkmcnt(0)
	v_mfma_f32_32x32x16_bf16 v[218:233], v[202:205], v[144:147], v[218:233]
	s_waitcnt lgkmcnt(9)
	v_mfma_f32_32x32x16_bf16 v[48:63], v[148:151], v[64:67], v[48:63]
	ds_read_b128 v[234:237], v96 offset:16384
	ds_read_b128 v[68:71], v96 offset:17408
	ds_read_b128 v[72:75], v96 offset:18432
	ds_read_b128 v[76:79], v96 offset:19456
	ds_read_b128 v[148:151], v96 offset:32768
	v_exp_f32_e32 v165, v165
	v_exp_f32_e32 v166, v166
	v_exp_f32_e32 v167, v167
	s_waitcnt lgkmcnt(13)
	v_mfma_f32_32x32x16_bf16 v[32:47], v[106:109], v[64:67], v[32:47]
	ds_read_b128 v[106:109], v96 offset:33792
	v_exp_f32_e32 v168, v168
	v_exp_f32_e32 v169, v169
	v_exp_f32_e32 v170, v170
	s_waitcnt lgkmcnt(12)
	v_mfma_f32_32x32x16_bf16 v[16:31], v[98:101], v[64:67], v[16:31]
	v_cvt_pk_bf16_f32 v98, v159, v111
	v_cvt_pk_bf16_f32 v99, v165, v166
	v_cvt_pk_bf16_f32 v100, v167, v168
	v_cvt_pk_bf16_f32 v101, v169, v170
	s_waitcnt lgkmcnt(13)
	v_mfma_f32_32x32x16_bf16 v[0:15], v[102:105], v[64:67], v[0:15]
	ds_read_b128 v[102:105], v96 offset:35840
	ds_read_b128 v[206:209], v96 offset:37888
	ds_read_b128 v[238:241], v96 offset:38912
	ds_read_b128 v[242:245], v96 offset:39936
	v_add_f32_e32 v183, v159, v183
	v_add_f32_e32 v183, v111, v183
	v_add_f32_e32 v183, v165, v183
	v_add_f32_e32 v183, v166, v183
	s_waitcnt lgkmcnt(9)
	v_mfma_f32_32x32x16_bf16 v[48:63], v[234:237], v[98:101], v[48:63]
	ds_read_b128 v[234:237], v96 offset:36864
	v_add_f32_e32 v183, v167, v183
	v_add_f32_e32 v183, v168, v183
	v_add_f32_e32 v183, v169, v183
	v_add_f32_e32 v183, v170, v183
	s_waitcnt lgkmcnt(9)
	v_mfma_f32_32x32x16_bf16 v[32:47], v[68:71], v[98:101], v[32:47]
	v_mov_b32_e32 v171, v183
	s_nop 1
	v_permlane32_swap_b32_e32 v183, v171
	s_waitcnt lgkmcnt(8)
	v_mfma_f32_32x32x16_bf16 v[16:31], v[72:75], v[98:101], v[16:31]
	v_add_f32_e32 v183, v183, v171
	v_add_f32_e32 v81, v81, v183
	s_waitcnt lgkmcnt(7)
	v_mfma_f32_32x32x16_bf16 v[0:15], v[76:79], v[98:101], v[0:15]
	ds_read_b128 v[98:101], v96 offset:34816
	v_lshl_add_u64 v[160:161], v[160:161], 0, s[26:27]
	v_lshl_add_u64 v[162:163], v[162:163], 0, s[28:29]
	s_cmp_eq_u32 s5, 34
	s_cbranch_scc1 .Lmy_exit
	s_mov_b32 s2, s5
	s_branch .LBB0_784

.Lmy_x791:
	v_fmamk_f32 v218, v218, 0x3dd53b94, v110
	v_fmamk_f32 v219, v219, 0x3dd53b94, v110
	v_exp_f32_e32 v218, v218
	v_fmamk_f32 v220, v220, 0x3dd53b94, v110
	v_exp_f32_e32 v219, v219
	v_add_f32_e32 v183, 0, v218
	v_fmamk_f32 v221, v221, 0x3dd53b94, v110
	v_exp_f32_e32 v220, v220
	v_add_f32_e32 v183, v219, v183
	v_fmamk_f32 v222, v222, 0x3dd53b94, v110
	v_exp_f32_e32 v221, v221
	v_add_f32_e32 v183, v220, v183
	v_fmamk_f32 v223, v223, 0x3dd53b94, v110
	v_exp_f32_e32 v222, v222
	v_add_f32_e32 v183, v221, v183
	v_fmamk_f32 v224, v224, 0x3dd53b94, v110
	v_exp_f32_e32 v223, v223
	v_add_f32_e32 v183, v222, v183
	v_fmamk_f32 v225, v225, 0x3dd53b94, v110
	v_exp_f32_e32 v224, v224
	v_add_f32_e32 v183, v223, v183
	v_exp_f32_e32 v225, v225
	v_add_f32_e32 v183, v224, v183
	v_add_f32_e32 v183, v225, v183
	v_fmamk_f32 v159, v226, 0x3dd53b94, v110
	v_fmamk_f32 v111, v227, 0x3dd53b94, v110
	v_fmamk_f32 v165, v228, 0x3dd53b94, v110
	v_fmamk_f32 v166, v229, 0x3dd53b94, v110
	v_cvt_pk_bf16_f32 v218, v218, v219
	v_cvt_pk_bf16_f32 v219, v220, v221
	v_fmamk_f32 v167, v230, 0x3dd53b94, v110
	v_fmamk_f32 v168, v231, 0x3dd53b94, v110
	v_fmamk_f32 v169, v232, 0x3dd53b94, v110
	v_fmac_f32_e32 v110, 0x3dd53b94, v233
	v_cvt_pk_bf16_f32 v220, v222, v223
	v_cvt_pk_bf16_f32 v221, v224, v225
	v_exp_f32_e32 v159, v159
	v_exp_f32_e32 v111, v111
	v_mfma_f32_32x32x16_bf16 v[48:63], v[148:151], v[218:221], v[48:63]
	v_exp_f32_e32 v165, v165
	v_exp_f32_e32 v166, v166
	v_exp_f32_e32 v167, v167
	v_mfma_f32_32x32x16_bf16 v[32:47], v[106:109], v[218:221], v[32:47]
	v_exp_f32_e32 v168, v168
	v_exp_f32_e32 v169, v169
	v_exp_f32_e32 v110, v110
	v_mfma_f32_32x32x16_bf16 v[16:31], v[98:101], v[218:221], v[16:31]
	v_cvt_pk_bf16_f32 v98, v159, v111
	v_cvt_pk_bf16_f32 v99, v165, v166
	v_cvt_pk_bf16_f32 v100, v167, v168
	v_cvt_pk_bf16_f32 v101, v169, v110
	v_mfma_f32_32x32x16_bf16 v[0:15], v[102:105], v[218:221], v[0:15]
	v_add_f32_e32 v183, v159, v183
	v_add_f32_e32 v183, v111, v183
	v_add_f32_e32 v183, v165, v183
	v_add_f32_e32 v183, v166, v183
	v_mfma_f32_32x32x16_bf16 v[48:63], v[234:237], v[98:101], v[48:63]
	v_add_f32_e32 v183, v167, v183
	v_add_f32_e32 v183, v168, v183
	v_add_f32_e32 v183, v169, v183
	v_add_f32_e32 v183, v110, v183
	v_mfma_f32_32x32x16_bf16 v[32:47], v[206:209], v[98:101], v[32:47]
	v_mov_b32_e32 v171, v183
	s_nop 1
	v_permlane32_swap_b32_e32 v183, v171
	v_mfma_f32_32x32x16_bf16 v[16:31], v[238:241], v[98:101], v[16:31]
	v_add_f32_e32 v183, v183, v171
	v_add_f32_e32 v81, v81, v183
	v_mfma_f32_32x32x16_bf16 v[0:15], v[242:245], v[98:101], v[0:15]
